# grid barrier between SSM pass 1 and pass 2 made XCD-local (wave end states are consumed inside the XCD); grouping check ordered strictly before it
# speedup vs baseline: 1.0032x; 1.0032x over previous
; __device__ __forceinline__ unsigned xb_add(unsigned* p, unsigned v) { return __hip_atomic_fetch_add(p, v, __ATOMIC_RELAXED, __HIP_MEMORY_SCOPE_AGENT); }
; __device__ __forceinline__ void xcd_barrier(const XcdBarrier& b) {
;     asm volatile("s_waitcnt vmcnt(0)" ::: "memory");
;     __syncthreads();
;     if (threadIdx.x == 0) {
;         unsigned* bar = b.bar;
;         __builtin_amdgcn_s_waitcnt(0);
;         unsigned nloc = b.st[0], nx = b.st[1];
;         if (nloc == 0u) { xcd_barrier_complete(bar, b.x, nloc, nx); b.st[0] = nloc; b.st[1] = nx; }
;         const unsigned old = xb_add(&bar[XB_XSUB(b.x)], 1u);
;         const unsigned gen = old / nloc;
;         if (old + 1u == (gen + 1u) * nloc) {
.LBB0_468:
	s_mov_b64 s[6:7], exec
	v_readlane_b32 s3, v254, 19
	s_lshl_b32 s3, s3, 8
	v_mbcnt_lo_u32_b32 v1, s6, 0
	s_add_u32 s4, s58, s3
	v_mbcnt_hi_u32_b32 v1, s7, v1
	s_addc_u32 s5, s59, 0
	v_cmp_eq_u32_e32 vcc, 0, v1
	s_and_saveexec_b64 s[8:9], vcc
	s_cbranch_execz .LBB0_470
	s_and_b32 s3, s2, 7
	s_lshl_b32 s3, s3, 2
	s_addk_i32 s3, 0x3700
	v_mov_b32_e32 v5, s3
	global_load_dword v5, v5, s[58:59] sc0 sc1
	s_waitcnt vmcnt(0)
	v_readfirstlane_b32 s10, v5
	v_readlane_b32 s11, v254, 19
	s_lshl_b32 s11, 1, s11
	s_cmp_eq_u32 s10, s11
	s_cbranch_scc1 .Lxgrp_ok
	v_mov_b32_e32 v5, 0x3780
	global_store_dword v5, v5, s[58:59] sc0 sc1
	s_waitcnt vmcnt(0)
.Lxgrp_ok:
	s_bcnt1_i32_b64 s3, s[6:7]
	v_mov_b32_e32 v3, 0x1000
	v_mov_b32_e32 v4, s3
	global_atomic_add v3, v3, v4, s[4:5] offset:1024 sc0

; __device__ __forceinline__ unsigned xb_ld(unsigned* p)              { return __hip_atomic_load(p, __ATOMIC_RELAXED, __HIP_MEMORY_SCOPE_AGENT); }
; __device__ __forceinline__ unsigned xb_add(unsigned* p, unsigned v) { return __hip_atomic_fetch_add(p, v, __ATOMIC_RELAXED, __HIP_MEMORY_SCOPE_AGENT); }
; #define XB_SPIN(cond, bar) do { unsigned _sp = 0; while (cond) { __builtin_amdgcn_s_sleep(1); \
;     if ((++_sp & 255u) == 0u) { if (xb_ld(&(bar)[XB_TMO])) break; if (_sp > XB_SPIN_CAP) { atomicAdd(&(bar)[XB_TMO], 1u); break; } } } } while (0)
; __device__ __forceinline__ void xcd_barrier(const XcdBarrier& b) {
;     ...
;         const unsigned old = xb_add(&bar[XB_XSUB(b.x)], 1u);
;         const unsigned gen = old / nloc;
;         if (old + 1u == (gen + 1u) * nloc) {
;             __builtin_amdgcn_fence(__ATOMIC_RELEASE, "agent");
;             asm volatile("s_waitcnt vmcnt(0)" ::: "memory");
;             const unsigned og = xb_add(&bar[XB_TOP], 1u);
;             const unsigned tg = og / nx;
;             if (og + 1u == (tg + 1u) * nx) xb_add(&bar[XB_TOPGEN], 1u);
;             else XB_SPIN(xb_ld(&bar[XB_TOPGEN]) == tg, bar);
.LBB0_584:
	s_andn2_saveexec_b64 s[6:7], s[6:7]
	s_cbranch_execz .LBB0_604
	s_mov_b64 s[6:7], exec
	v_readlane_b32 s3, v255, 40
	s_waitcnt lgkmcnt(0)
	s_cmp_eq_u32 s3, 0
	s_cbranch_scc1 .Lxloc_2
	buffer_wbl2 sc1
	s_waitcnt lgkmcnt(0)
	s_waitcnt vmcnt(0)
	v_mbcnt_lo_u32_b32 v1, s6, 0
	v_mbcnt_hi_u32_b32 v1, s7, v1
	v_cmp_eq_u32_e32 vcc, 0, v1
	s_and_saveexec_b64 s[8:9], vcc
	s_cbranch_execz .LBB0_587
	s_bcnt1_i32_b64 s3, s[6:7]
	v_mov_b32_e32 v2, 0x3000
	v_mov_b32_e32 v3, s3
	global_atomic_add v2, v2, v3, s[58:59] offset:1024 sc0

; __device__ __forceinline__ unsigned xb_add(unsigned* p, unsigned v) { return __hip_atomic_fetch_add(p, v, __ATOMIC_RELAXED, __HIP_MEMORY_SCOPE_AGENT); }
; __device__ __forceinline__ void xcd_barrier(const XcdBarrier& b) {
;     ...
;             __builtin_amdgcn_fence(__ATOMIC_ACQUIRE, "agent");
;             xb_add(&bar[XB_XGEN(b.x)], 1u);
;             asm volatile("s_waitcnt vmcnt(0)" ::: "memory");
.Lxloc_2:
	s_mov_b64 s[6:7], exec
	v_mbcnt_lo_u32_b32 v0, s6, 0
	v_mbcnt_hi_u32_b32 v0, s7, v0
	v_cmp_eq_u32_e32 vcc, 0, v0
	s_waitcnt vmcnt(0)
	buffer_inv sc1
	s_and_saveexec_b64 s[8:9], vcc
	s_cbranch_execz .LBB0_603
	s_bcnt1_i32_b64 s3, s[6:7]
	v_mov_b32_e32 v0, 0x2000
	v_mov_b32_e32 v1, s3
	global_atomic_add v0, v1, s[4:5] offset:1024
